# sw phase row loads prefetched one row ahead; norm phases issue all gain/scale loads at once
# speedup vs baseline: 1.0022x; 1.0022x over previous
; __device__ __forceinline__ void sw_phase(const unsigned char* ws, const float* MOD, float* SW) {
;     ...
;     for (int mtx = 0; mtx < 12; ++mtx) {
;         const int l = mtx / 3, sub = mtx % 3, N = sub == 1 ? INW : 2 * DFF;
;         const bf16* Bt = sub == 1 ? (const bf16*)(ws + WS_WIN) + (size_t)l * INW * DM : (const bf16*)(ws + WS_WUP) + (size_t)(l * 2 + (sub >> 1)) * 2 * DFF * DM;
;         const float* sh = MOD + (size_t)l * 5 * MODW + 3 * sub * DM + lane * 16;
;         f32x4 shv[5][4];
; #pragma unroll
;         for (int c = 0; c < 5; ++c)
; #pragma unroll
;             for (int j = 0; j < 4; ++j) shv[c][j] = *(const f32x4*)(sh + (size_t)c * MODW + 4 * j);
;         for (int n = gw; n < N; n += NGW) {
;             const v4u w0 = *(const v4u*)(Bt + (size_t)n * DM + lane * 16), w1 = *(const v4u*)(Bt + (size_t)n * DM + lane * 16 + 8);
.LBB0_77:
	s_mul_i32 s34, s34, 0x2d000
	s_add_u32 s30, s58, s34
	s_addc_u32 s31, s59, 0
	s_mulk_i32 s35, 0x3000
	s_add_u32 s30, s30, s35
	s_addc_u32 s31, s31, 0
	v_lshl_add_u64 v[40:41], s[30:31], 0, v[80:81]
	v_add_co_u32_e32 v0, vcc, s33, v40
	v_lshl_add_u64 v[12:13], v[40:41], 0, s[18:19]
	s_nop 0
	v_addc_co_u32_e32 v1, vcc, 0, v41, vcc
	v_add_co_u32_e32 v16, vcc, s38, v40
	v_lshl_add_u64 v[28:29], v[40:41], 0, s[20:21]
	s_nop 0
	v_addc_co_u32_e32 v17, vcc, 0, v41, vcc
	v_add_co_u32_e32 v32, vcc, s39, v40
	v_lshl_add_u64 v[44:45], v[40:41], 0, s[22:23]
	s_nop 0
	v_addc_co_u32_e32 v33, vcc, 0, v41, vcc
	v_add_co_u32_e32 v48, vcc, s40, v40
	v_lshl_add_u64 v[60:61], v[40:41], 0, s[24:25]
	s_nop 0
	v_addc_co_u32_e32 v49, vcc, 0, v41, vcc
	global_load_dwordx4 v[0:3], v[0:1], off
	s_nop 0
	global_load_dwordx4 v[4:7], v[12:13], off offset:48
	global_load_dwordx4 v[8:11], v[12:13], off offset:32
	s_nop 0
	global_load_dwordx4 v[12:15], v[12:13], off offset:16
	s_nop 0
	global_load_dwordx4 v[16:19], v[16:17], off
	s_nop 0
	global_load_dwordx4 v[20:23], v[28:29], off offset:48
	global_load_dwordx4 v[24:27], v[28:29], off offset:32
	s_nop 0
	global_load_dwordx4 v[28:31], v[28:29], off offset:16
	s_nop 0
	global_load_dwordx4 v[32:35], v[32:33], off
	s_nop 0
	global_load_dwordx4 v[36:39], v[44:45], off offset:48
	global_load_dwordx4 v[40:43], v[44:45], off offset:32
	s_nop 0
	global_load_dwordx4 v[44:47], v[44:45], off offset:16
	s_nop 0
	global_load_dwordx4 v[48:51], v[48:49], off
	s_nop 0
	global_load_dwordx4 v[52:55], v[60:61], off offset:48
	global_load_dwordx4 v[56:59], v[60:61], off offset:32
	s_nop 0
	global_load_dwordx4 v[60:63], v[60:61], off offset:16
	s_nop 0
	global_load_dwordx4 v[64:67], v80, s[30:31] offset:48
	global_load_dwordx4 v[68:71], v80, s[30:31] offset:32
	global_load_dwordx4 v[72:75], v80, s[30:31] offset:16
	global_load_dwordx4 v[76:79], v80, s[30:31]
	v_cmp_lt_i32_e32 vcc, v199, v198
	s_lshl_b64 s[30:31], s[14:15], 1
	s_add_u32 s28, s28, s30
	v_cndmask_b32_e32 v86, v197, v199, vcc
	v_cmp_lt_i32_e32 vcc, v200, v198
	v_lshlrev_b32_e32 v91, 2, v86
	s_addc_u32 s29, s29, s31
	v_cndmask_b32_e32 v86, v197, v200, vcc
	v_cmp_lt_i32_e32 vcc, v201, v198
	v_lshlrev_b32_e32 v92, 2, v86
	s_mov_b32 s14, s16
	v_cndmask_b32_e32 v86, v197, v201, vcc
	v_cmp_lt_i32_e32 vcc, v202, v198
	v_lshlrev_b32_e32 v93, 2, v86
	v_mov_b64_e32 v[88:89], v[82:83]
	v_cndmask_b32_e32 v86, v197, v202, vcc
	v_cmp_lt_i32_e32 vcc, v203, v198
	v_lshlrev_b32_e32 v94, 2, v86
	s_nop 0
	v_cndmask_b32_e32 v86, v197, v203, vcc
	v_cmp_lt_i32_e32 vcc, v204, v198
	v_lshlrev_b32_e32 v95, 2, v86
	s_nop 0
	v_cndmask_b32_e32 v86, v197, v204, vcc
	v_lshlrev_b32_e32 v96, 2, v86
	v_lshl_add_u64 v[86:87], v[84:85], 0, s[28:29]
	global_load_dwordx4 v[130:133], v[86:87], off offset:-16
	global_load_dwordx4 v[134:137], v[86:87], off
	s_branch .LBB0_81

; __device__ __forceinline__ void sw_phase(const unsigned char* ws, const float* MOD, float* SW) {
;     ...
;         for (int n = gw; n < N; n += NGW) {
;             const v4u w0 = *(const v4u*)(Bt + (size_t)n * DM + lane * 16), w1 = *(const v4u*)(Bt + (size_t)n * DM + lane * 16 + 8);
;             f32x4 wf[4];
;             wf[0] = (f32x4){__uint_as_float(w0.x << 16), __uint_as_float(w0.x & 0xffff0000u), __uint_as_float(w0.y << 16), __uint_as_float(w0.y & 0xffff0000u)};
;             wf[1] = (f32x4){__uint_as_float(w0.z << 16), __uint_as_float(w0.z & 0xffff0000u), __uint_as_float(w0.w << 16), __uint_as_float(w0.w & 0xffff0000u)};
;             wf[2] = (f32x4){__uint_as_float(w1.x << 16), __uint_as_float(w1.x & 0xffff0000u), __uint_as_float(w1.y << 16), __uint_as_float(w1.y & 0xffff0000u)};
;             wf[3] = (f32x4){__uint_as_float(w1.z << 16), __uint_as_float(w1.z & 0xffff0000u), __uint_as_float(w1.w << 16), __uint_as_float(w1.w & 0xffff0000u)};
;             float d[5];
; #pragma unroll
;             for (int c = 0; c < 5; ++c) { f32x4 a = shv[c][0] * wf[0] + shv[c][1] * wf[1] + shv[c][2] * wf[2] + shv[c][3] * wf[3]; d[c] = wave_sum((a[0] + a[1]) + (a[2] + a[3])); }
;             if (lane < 5) { const float v = lane == 0 ? d[0] : lane == 1 ? d[1] : lane == 2 ? d[2] : lane == 3 ? d[3] : d[4]; SW[((size_t)mtx * 5 + lane) * (2 * DFF) + n] = v; }
.LBB0_81:
	s_waitcnt lgkmcnt(0)
	v_lshl_add_u64 v[138:139], v[86:87], 0, s[12:13]
	s_waitcnt vmcnt(0)
	v_mov_b32_e32 v98, v130
	v_mov_b32_e32 v99, v131
	v_mov_b32_e32 v100, v132
	v_mov_b32_e32 v101, v133
	v_mov_b32_e32 v102, v134
	v_mov_b32_e32 v103, v135
	v_mov_b32_e32 v104, v136
	v_mov_b32_e32 v105, v137
	global_load_dwordx4 v[130:133], v[138:139], off offset:-16
	global_load_dwordx4 v[134:137], v[138:139], off
	v_lshlrev_b32_e32 v108, 16, v100
	v_and_b32_e32 v109, 0xffff0000, v100
	v_lshlrev_b32_e32 v100, 16, v101
	v_and_b32_e32 v101, 0xffff0000, v101
	v_lshlrev_b32_e32 v106, 16, v98
	v_and_b32_e32 v107, 0xffff0000, v98
	v_lshlrev_b32_e32 v98, 16, v99
	v_and_b32_e32 v99, 0xffff0000, v99
	v_pk_mul_f32 v[114:115], v[72:73], v[108:109]
	v_pk_mul_f32 v[116:117], v[74:75], v[100:101]
	v_pk_mul_f32 v[118:119], v[12:13], v[108:109]
	v_pk_mul_f32 v[120:121], v[14:15], v[100:101]
	v_lshlrev_b32_e32 v110, 16, v102
	v_and_b32_e32 v111, 0xffff0000, v102
	v_lshlrev_b32_e32 v102, 16, v103
	v_and_b32_e32 v103, 0xffff0000, v103
	v_pk_mul_f32 v[122:123], v[28:29], v[108:109]
	v_pk_mul_f32 v[124:125], v[30:31], v[100:101]
	v_pk_mul_f32 v[126:127], v[44:45], v[108:109]
	v_pk_mul_f32 v[128:129], v[46:47], v[100:101]
	v_pk_mul_f32 v[108:109], v[60:61], v[108:109]
	v_pk_mul_f32 v[100:101], v[62:63], v[100:101]
	v_pk_fma_f32 v[116:117], v[78:79], v[98:99], v[116:117]
	v_pk_fma_f32 v[114:115], v[76:77], v[106:107], v[114:115]
	v_pk_fma_f32 v[120:121], v[2:3], v[98:99], v[120:121]
	v_pk_fma_f32 v[118:119], v[0:1], v[106:107], v[118:119]
	v_lshlrev_b32_e32 v112, 16, v104
	v_and_b32_e32 v113, 0xffff0000, v104
	v_lshlrev_b32_e32 v104, 16, v105
	v_and_b32_e32 v105, 0xffff0000, v105
	v_pk_fma_f32 v[124:125], v[18:19], v[98:99], v[124:125]
	v_pk_fma_f32 v[122:123], v[16:17], v[106:107], v[122:123]
	v_pk_fma_f32 v[128:129], v[34:35], v[98:99], v[128:129]
	v_pk_fma_f32 v[126:127], v[32:33], v[106:107], v[126:127]
	v_pk_fma_f32 v[98:99], v[50:51], v[98:99], v[100:101]
	v_pk_fma_f32 v[100:101], v[48:49], v[106:107], v[108:109]
	v_pk_fma_f32 v[106:107], v[68:69], v[110:111], v[114:115]
	v_pk_fma_f32 v[108:109], v[70:71], v[102:103], v[116:117]
	v_pk_fma_f32 v[114:115], v[8:9], v[110:111], v[118:119]
	v_pk_fma_f32 v[116:117], v[10:11], v[102:103], v[120:121]
	v_pk_fma_f32 v[118:119], v[24:25], v[110:111], v[122:123]
	v_pk_fma_f32 v[120:121], v[26:27], v[102:103], v[124:125]
	v_pk_fma_f32 v[122:123], v[40:41], v[110:111], v[126:127]
	v_pk_fma_f32 v[124:125], v[42:43], v[102:103], v[128:129]
	v_pk_fma_f32 v[100:101], v[56:57], v[110:111], v[100:101]
	v_pk_fma_f32 v[98:99], v[58:59], v[102:103], v[98:99]
	v_pk_fma_f32 v[102:103], v[66:67], v[104:105], v[108:109]
	v_pk_fma_f32 v[108:109], v[6:7], v[104:105], v[116:117]
	v_pk_fma_f32 v[110:111], v[4:5], v[112:113], v[114:115]
	v_pk_fma_f32 v[114:115], v[22:23], v[104:105], v[120:121]
	v_pk_fma_f32 v[116:117], v[20:21], v[112:113], v[118:119]
	v_pk_fma_f32 v[118:119], v[38:39], v[104:105], v[124:125]
	v_pk_fma_f32 v[98:99], v[54:55], v[104:105], v[98:99]
	v_add_f32_e32 v102, v102, v103
	v_add_f32_e32 v103, v110, v111
	v_add_f32_e32 v104, v108, v109
	v_add_f32_e32 v98, v98, v99
	v_add_f32_e32 v99, v103, v104
	ds_bpermute_b32 v103, v91, v99
	v_pk_fma_f32 v[106:107], v[64:65], v[112:113], v[106:107]
	v_pk_fma_f32 v[120:121], v[36:37], v[112:113], v[122:123]
	v_pk_fma_f32 v[100:101], v[52:53], v[112:113], v[100:101]
	v_add_f32_e32 v97, v106, v107
	v_add_f32_e32 v105, v116, v117
	v_add_f32_e32 v106, v114, v115
	v_add_f32_e32 v107, v120, v121
	v_add_f32_e32 v108, v118, v119
	v_add_f32_e32 v100, v100, v101
	v_add_f32_e32 v97, v97, v102
	v_add_f32_e32 v101, v105, v106
	v_add_f32_e32 v102, v107, v108
	v_add_f32_e32 v98, v100, v98
	ds_bpermute_b32 v100, v91, v97
	ds_bpermute_b32 v104, v91, v101
	ds_bpermute_b32 v105, v91, v102
	ds_bpermute_b32 v106, v91, v98
	s_waitcnt lgkmcnt(4)
	v_add_f32_e32 v99, v99, v103
	ds_bpermute_b32 v103, v92, v99
	s_waitcnt lgkmcnt(4)
	v_add_f32_e32 v97, v97, v100
	s_waitcnt lgkmcnt(3)
	v_add_f32_e32 v100, v101, v104
	s_waitcnt lgkmcnt(2)
	v_add_f32_e32 v101, v102, v105
	s_waitcnt lgkmcnt(1)
	v_add_f32_e32 v98, v98, v106
	ds_bpermute_b32 v102, v92, v97
	ds_bpermute_b32 v104, v92, v100
	ds_bpermute_b32 v105, v92, v101
	ds_bpermute_b32 v106, v92, v98
	s_waitcnt lgkmcnt(4)
	v_add_f32_e32 v99, v99, v103
	ds_bpermute_b32 v103, v93, v99
	s_waitcnt lgkmcnt(4)
	v_add_f32_e32 v97, v97, v102
	s_waitcnt lgkmcnt(3)
	v_add_f32_e32 v100, v100, v104
	s_waitcnt lgkmcnt(2)
	v_add_f32_e32 v101, v101, v105
	s_waitcnt lgkmcnt(1)
	v_add_f32_e32 v98, v98, v106
	ds_bpermute_b32 v102, v93, v97
	ds_bpermute_b32 v104, v93, v100
	ds_bpermute_b32 v105, v93, v101
	ds_bpermute_b32 v106, v93, v98
	s_waitcnt lgkmcnt(4)
	v_add_f32_e32 v99, v99, v103
	ds_bpermute_b32 v103, v94, v99
	s_waitcnt lgkmcnt(4)
	v_add_f32_e32 v97, v97, v102
	s_waitcnt lgkmcnt(3)
	v_add_f32_e32 v100, v100, v104
	s_waitcnt lgkmcnt(2)
	v_add_f32_e32 v102, v101, v105
	s_waitcnt lgkmcnt(1)
	v_add_f32_e32 v98, v98, v106
	ds_bpermute_b32 v101, v94, v97
	ds_bpermute_b32 v104, v94, v100
	ds_bpermute_b32 v105, v94, v102
	s_waitcnt lgkmcnt(3)
	v_add_f32_e32 v99, v99, v103
	ds_bpermute_b32 v107, v94, v98
	ds_bpermute_b32 v103, v95, v99
	s_waitcnt lgkmcnt(4)
	v_add_f32_e32 v97, v97, v101
	s_waitcnt lgkmcnt(3)
	v_add_f32_e32 v104, v100, v104
	s_waitcnt lgkmcnt(2)
	v_add_f32_e32 v102, v102, v105
	s_waitcnt lgkmcnt(1)
	v_add_f32_e32 v105, v98, v107
	ds_bpermute_b32 v101, v95, v97
	ds_bpermute_b32 v108, v95, v104
	s_waitcnt lgkmcnt(2)
	v_add_f32_e32 v100, v99, v103
	ds_bpermute_b32 v103, v95, v102
	ds_bpermute_b32 v107, v95, v105
	s_waitcnt lgkmcnt(3)
	v_add_f32_e32 v97, v97, v101
	s_waitcnt lgkmcnt(2)
	v_add_f32_e32 v98, v104, v108
	ds_bpermute_b32 v106, v96, v97
	s_waitcnt lgkmcnt(2)
	v_add_f32_e32 v102, v102, v103
	s_waitcnt lgkmcnt(1)
	v_add_f32_e32 v104, v105, v107
	ds_bpermute_b32 v101, v96, v100
	ds_bpermute_b32 v99, v96, v98
	ds_bpermute_b32 v103, v96, v102
	ds_bpermute_b32 v105, v96, v104
	s_and_saveexec_b64 s[28:29], s[4:5]
	s_cbranch_execz .LBB0_80
	s_waitcnt lgkmcnt(4)
	v_add_f32_e32 v97, v97, v106
	v_cmp_lt_i32_e32 vcc, 0, v90
	s_and_saveexec_b64 s[30:31], vcc
	s_cbranch_execz .LBB0_79
	v_cmp_lt_i32_e32 vcc, 1, v90
	s_and_saveexec_b64 s[34:35], vcc
	s_xor_b64 s[34:35], exec, s[34:35]
	s_cbranch_execz .LBB0_89
	v_cmp_ne_u32_e32 vcc, 2, v90
	s_and_saveexec_b64 s[36:37], vcc
	s_xor_b64 s[36:37], exec, s[36:37]
	s_cbranch_execz .LBB0_86
	s_waitcnt lgkmcnt(1)
	v_add_f32_e32 v97, v102, v103
	s_waitcnt lgkmcnt(0)
	v_add_f32_e32 v98, v104, v105
	v_cndmask_b32_e64 v97, v98, v97, s[6:7]

; __device__ __forceinline__ unsigned pk2(float lo, float hi) { return __builtin_bit_cast(unsigned, __builtin_convertvector((f32x2_t){lo, hi}, bf16x2_t)); }
; __device__ __forceinline__ void norm_phase(const float* xlat, const float* xctx, float* XC, const float* P, int npart, bf16* H, float* SS, const float* g, const float* modl, int jshift, int row_begin, int Mrows) {
;     ...
;         const float* sh = modl + (size_t)cond * MODW + jshift * DM; const float* scl = sh + DM;
;         unsigned long long* o8 = (unsigned long long*)(H + (size_t)row * DM) + lane;
; #pragma unroll
;         for (int j = 0; j < 4; ++j) { const f32x4 gg = *((const f32x4*)g + lane + 64 * j), s4 = *((const f32x4*)scl + lane + 64 * j);
;             const f32x4 o = v[j] * gg * (1.0f + s4);
;             o8[64 * j] = (unsigned long long)pk2(o[0], o[1]) | ((unsigned long long)pk2(o[2], o[3]) << 32); }
.LBB0_93:
	s_or_b64 exec, exec, s[18:19]
	s_min_i32 s14, s6, 0x8000
	s_ashr_i32 s14, s14, 13
	s_mul_hi_i32 s19, s14, 0x9000
	s_mul_i32 s14, s14, 0x9000
	s_add_u32 s18, s58, s14
	s_addc_u32 s19, s59, s19
	v_lshl_add_u64 v[40:41], s[18:19], 0, v[16:17]
	v_add_co_u32_e32 v36, vcc, s23, v40
	s_waitcnt lgkmcnt(0)
	global_load_dwordx4 v[32:35], v[20:21], off
	v_addc_co_u32_e32 v37, vcc, 0, v41, vcc
	global_load_dwordx4 v[36:39], v[36:37], off
	v_lshl_add_u64 v[58:59], v[40:41], 0, s[16:17]
	global_load_dwordx4 v[60:63], v[20:21], off offset:1024
	global_load_dwordx4 v[64:67], v[58:59], off offset:1024
	global_load_dwordx4 v[68:71], v[20:21], off offset:2048
	global_load_dwordx4 v[72:75], v[58:59], off offset:2048
	global_load_dwordx4 v[76:79], v[20:21], off offset:3072
	global_load_dwordx4 v[44:47], v[58:59], off offset:3072
	v_lshl_add_u64 v[42:43], s[58:59], 0, v[22:23]
	v_add_co_u32_e32 v42, vcc, s24, v42
	s_add_u32 s6, s6, s84
	s_nop 0
	v_addc_co_u32_e32 v43, vcc, 0, v43, vcc
	s_addc_u32 s7, s7, s85
	s_add_u32 s20, s20, s10
	s_addc_u32 s21, s21, s11
	s_cmp_lt_i32 s6, 0x8400
	v_lshl_add_u64 v[22:23], v[22:23], 0, s[12:13]
	s_waitcnt vmcnt(7)
	v_pk_mul_f32 v[14:15], v[14:15], v[34:35]
	v_pk_mul_f32 v[12:13], v[12:13], v[32:33]
	s_waitcnt vmcnt(6)
	v_pk_add_f32 v[32:33], v[38:39], 1.0 op_sel_hi:[1,0]
	v_pk_add_f32 v[34:35], v[36:37], 1.0 op_sel_hi:[1,0]
	v_pk_mul_f32 v[14:15], v[14:15], v[32:33]
	v_pk_mul_f32 v[12:13], v[12:13], v[34:35]
	v_lshl_add_u64 v[36:37], v[40:41], 0, s[16:17]
	v_cvt_pk_bf16_f32 v12, v12, v13
	v_cvt_pk_bf16_f32 v13, v14, v15
	global_store_dwordx2 v[42:43], v[12:13], off
	s_waitcnt vmcnt(6)
	v_pk_mul_f32 v[10:11], v[10:11], v[62:63]
	v_pk_mul_f32 v[8:9], v[8:9], v[60:61]
	s_waitcnt vmcnt(5)
	v_pk_add_f32 v[12:13], v[66:67], 1.0 op_sel_hi:[1,0]
	v_pk_add_f32 v[14:15], v[64:65], 1.0 op_sel_hi:[1,0]
	v_pk_mul_f32 v[10:11], v[10:11], v[12:13]
	v_pk_mul_f32 v[8:9], v[8:9], v[14:15]
	s_nop 0
	v_cvt_pk_bf16_f32 v8, v8, v9
	v_cvt_pk_bf16_f32 v9, v10, v11
	global_store_dwordx2 v[42:43], v[8:9], off offset:512
	s_nop 0
	s_waitcnt vmcnt(5)
	v_pk_mul_f32 v[6:7], v[6:7], v[70:71]
	v_pk_mul_f32 v[4:5], v[4:5], v[68:69]
	s_waitcnt vmcnt(4)
	v_pk_add_f32 v[8:9], v[74:75], 1.0 op_sel_hi:[1,0]
	v_pk_add_f32 v[10:11], v[72:73], 1.0 op_sel_hi:[1,0]
	v_pk_mul_f32 v[6:7], v[6:7], v[8:9]
	v_pk_mul_f32 v[4:5], v[4:5], v[10:11]
	s_nop 0
	v_cvt_pk_bf16_f32 v4, v4, v5
	v_cvt_pk_bf16_f32 v5, v6, v7
	global_store_dwordx2 v[42:43], v[4:5], off offset:1024
	s_nop 0
	s_waitcnt vmcnt(4)
	v_pk_mul_f32 v[2:3], v[2:3], v[78:79]
	v_pk_mul_f32 v[0:1], v[0:1], v[76:77]
	s_waitcnt vmcnt(3)
	v_pk_add_f32 v[4:5], v[46:47], 1.0 op_sel_hi:[1,0]
	v_pk_add_f32 v[6:7], v[44:45], 1.0 op_sel_hi:[1,0]
	v_pk_mul_f32 v[2:3], v[2:3], v[4:5]
	v_pk_mul_f32 v[0:1], v[0:1], v[6:7]
	s_nop 0
	v_cvt_pk_bf16_f32 v0, v0, v1
	v_cvt_pk_bf16_f32 v1, v2, v3
	global_store_dwordx2 v[42:43], v[0:1], off offset:1536
	s_cbranch_scc0 .LBB0_98

; __device__ __forceinline__ unsigned pk2(float lo, float hi) { return __builtin_bit_cast(unsigned, __builtin_convertvector((f32x2_t){lo, hi}, bf16x2_t)); }
; __device__ __forceinline__ void norm_phase(const float* xlat, const float* xctx, float* XC, const float* P, int npart, bf16* H, float* SS, const float* g, const float* modl, int jshift, int row_begin, int Mrows) {
;     ...
;         const float* sh = modl + (size_t)cond * MODW + jshift * DM; const float* scl = sh + DM;
;         unsigned long long* o8 = (unsigned long long*)(H + (size_t)row * DM) + lane;
; #pragma unroll
;         for (int j = 0; j < 4; ++j) { const f32x4 gg = *((const f32x4*)g + lane + 64 * j), s4 = *((const f32x4*)scl + lane + 64 * j);
;             const f32x4 o = v[j] * gg * (1.0f + s4);
;             o8[64 * j] = (unsigned long long)pk2(o[0], o[1]) | ((unsigned long long)pk2(o[2], o[3]) << 32); }
; __global__ void __launch_bounds__(NWAVES * 64, 2) fwd_mega(Params p) {
;     ...
;                 if (Mrows > MLAT) norm_phase(xlat, xctx, XC, (const float*)(ws + WS_P), sub == 2 ? 4 : 11, Hs, RF, p.norm_g + (size_t)(l * 3 + sub) * DM, modl, 3 * sub, MLAT, Mrows);
.LBB0_165:
	s_or_b64 exec, exec, s[30:31]
	s_min_i32 s12, s26, 0x8000
	s_ashr_i32 s12, s12, 13
	s_mul_hi_i32 s13, s12, 0x9000
	s_mul_i32 s12, s12, 0x9000
	s_add_u32 s12, s10, s12
	s_addc_u32 s13, s11, s13
	v_mov_b32_e32 v27, v80
	v_lshl_add_u64 v[40:41], s[12:13], 0, v[26:27]
	v_add_co_u32_e32 v36, vcc, s49, v40
	s_waitcnt lgkmcnt(0)
	global_load_dwordx4 v[26:29], v[22:23], off
	v_addc_co_u32_e32 v37, vcc, 0, v41, vcc
	global_load_dwordx4 v[36:39], v[36:37], off
	s_lshl_b64 s[12:13], s[26:27], 11
	v_lshl_add_u64 v[42:43], v[20:21], 0, s[12:13]
	s_mov_b64 s[12:13], 0x1000
	v_lshl_add_u64 v[58:59], v[40:41], 0, s[12:13]
	global_load_dwordx4 v[60:63], v[22:23], off offset:1024
	global_load_dwordx4 v[64:67], v[58:59], off offset:1024
	global_load_dwordx4 v[68:71], v[22:23], off offset:2048
	global_load_dwordx4 v[72:75], v[58:59], off offset:2048
	global_load_dwordx4 v[76:79], v[22:23], off offset:3072
	global_load_dwordx4 v[44:47], v[58:59], off offset:3072
	s_add_i32 s26, s26, s84
	s_add_i32 s28, s28, s84
	s_cmp_lt_i32 s26, s2
	s_waitcnt vmcnt(7)
	v_pk_mul_f32 v[14:15], v[14:15], v[28:29]
	v_pk_mul_f32 v[12:13], v[12:13], v[26:27]
	s_waitcnt vmcnt(6)
	v_pk_add_f32 v[26:27], v[38:39], 1.0 op_sel_hi:[1,0]
	v_pk_add_f32 v[28:29], v[36:37], 1.0 op_sel_hi:[1,0]
	v_pk_mul_f32 v[14:15], v[14:15], v[26:27]
	v_pk_mul_f32 v[12:13], v[12:13], v[28:29]
	v_lshl_add_u64 v[36:37], v[40:41], 0, s[12:13]
	v_cvt_pk_bf16_f32 v12, v12, v13
	v_cvt_pk_bf16_f32 v13, v14, v15
	global_store_dwordx2 v[42:43], v[12:13], off
	s_waitcnt vmcnt(6)
	v_pk_mul_f32 v[10:11], v[10:11], v[62:63]
	v_pk_mul_f32 v[8:9], v[8:9], v[60:61]
	s_waitcnt vmcnt(5)
	v_pk_add_f32 v[12:13], v[66:67], 1.0 op_sel_hi:[1,0]
	v_pk_add_f32 v[14:15], v[64:65], 1.0 op_sel_hi:[1,0]
	v_pk_mul_f32 v[10:11], v[10:11], v[12:13]
	v_pk_mul_f32 v[8:9], v[8:9], v[14:15]
	s_nop 0
	v_cvt_pk_bf16_f32 v8, v8, v9
	v_cvt_pk_bf16_f32 v9, v10, v11
	global_store_dwordx2 v[42:43], v[8:9], off offset:512
	s_nop 0
	s_waitcnt vmcnt(5)
	v_pk_mul_f32 v[6:7], v[6:7], v[70:71]
	v_pk_mul_f32 v[4:5], v[4:5], v[68:69]
	s_waitcnt vmcnt(4)
	v_pk_add_f32 v[8:9], v[74:75], 1.0 op_sel_hi:[1,0]
	v_pk_add_f32 v[10:11], v[72:73], 1.0 op_sel_hi:[1,0]
	v_pk_mul_f32 v[6:7], v[6:7], v[8:9]
	v_pk_mul_f32 v[4:5], v[4:5], v[10:11]
	s_nop 0
	v_cvt_pk_bf16_f32 v4, v4, v5
	v_cvt_pk_bf16_f32 v5, v6, v7
	global_store_dwordx2 v[42:43], v[4:5], off offset:1024
	s_nop 0
	s_waitcnt vmcnt(4)
	v_pk_mul_f32 v[2:3], v[2:3], v[78:79]
	v_pk_mul_f32 v[0:1], v[0:1], v[76:77]
	s_waitcnt vmcnt(3)
	v_pk_add_f32 v[4:5], v[46:47], 1.0 op_sel_hi:[1,0]
	v_pk_add_f32 v[6:7], v[44:45], 1.0 op_sel_hi:[1,0]
	v_pk_mul_f32 v[2:3], v[2:3], v[4:5]
	v_pk_mul_f32 v[0:1], v[0:1], v[6:7]
	s_nop 0
	v_cvt_pk_bf16_f32 v0, v0, v1
	v_cvt_pk_bf16_f32 v1, v2, v3
	global_store_dwordx2 v[42:43], v[0:1], off offset:1536
	s_cbranch_scc0 .LBB0_172
